# v093 + DQ128 attention-unit prologue issues the first K/V LDS-DMA right after the Q loads (vmcnt of Q-certifying waits +8)
# speedup vs baseline: 1.0050x; 1.0022x over previous
; __device__ __forceinline__ int v_rd_base(int lane) { return ((lane & 3) << 3) | (((lane >> 2) & 3) << 6) | (((lane >> 4) & 1) << 5) | (((lane >> 5) & 1) << 8); }
; template <int DQ, int MODE>
; __device__ __forceinline__ void attn_unit(const Args& a, char* lds, const int wave0) {
;     ...
;   const bf16* Qw = a.Q + (long)(wid * QBLK + r32) * a.ldq + hi * 8;
; #pragma unroll
;   for (int d0 = 0; d0 < NQ; ++d0) qr[d0] = *reinterpret_cast<const bf16x8*>(Qw + d0 * 16);
;     ...
;   const int vb0 = (int)(uintptr_t)V_lds + v_rd_base(lane);
;   int kx[4];
; #pragma unroll
;   for (int q = 0; q < 4; ++q) kx[q] = (int)(uintptr_t)K_lds + r32 * (DQ * 2) + ((q * 32 + hi * 16) ^ ((r32 & 7) << 4));
;   constexpr int KP = DQ / 64;
;   int koff[KP]; bool kk2[KP]; int voff[2];
; #pragma unroll
;   for (int i = 0; i < KP; ++i) { const int q = (wid * KP + i) * 64 + lane, row = q / (DQ / 8), cs = q % (DQ / 8), c = cs ^ (row & 7);
;     kk2[i] = (DQ == 192) && c >= 16; koff[i] = kk2[i] ? row * a.ldk2 + (c - 16) * 8 : row * a.ldk + c * 8; }
; #pragma unroll
;   for (int i = 0; i < 2; ++i) { const int q = (wid * 2 + i) * 64 + lane, sub = q >> 5, within = q & 31, kk = (sub >> 2) * 8 + (within >> 2), c = (sub & 3) * 32 + (within & 3) * 8;
;     const int k = kk; voff[i] = k * a.ldv + c; }
;   const unsigned kdst0 = (unsigned)(uintptr_t)K_lds + (unsigned)(wid * KP) * 1024u, vdst0 = (unsigned)(uintptr_t)V_lds + (unsigned)(wid * 2) * 1024u;
;     ...
;   f32x16 pA0, pA1, pB0, pB1; float mnA, mnB, alA, alB; bf16x8 pa0, pa1, pa2, pa3; const int NT = a.NT;
;     ...
;   DMA(0); DMA(1);
.LBB0_765:
	s_cbranch_execz .LBB0_720
	s_mul_i32 s5, s30, 0x1600
	s_mul_hi_u32 s4, s30, 0x1600
	s_add_u32 s5, s2, s5
	s_addc_u32 s6, s48, s4
	s_lshl_b32 s4, s65, 8
	v_mbcnt_lo_u32_b32 v73, -1, 0
	v_mbcnt_hi_u32_b32 v73, -1, v73
	s_add_u32 s4, s5, s4
	v_add_u32_e32 v72, s93, v73
	v_ashrrev_i32_e32 v169, 6, v72
	s_addc_u32 s5, s6, 0
	v_and_b32_e32 v161, 31, v73
	v_lshlrev_b32_e32 v160, 5, v169
	v_bfe_u32 v168, v73, 5, 1
	v_or_b32_e32 v75, v160, v161
	v_mov_b64_e32 v[0:1], s[4:5]
	s_movk_i32 s4, 0x1600
	v_mad_i64_i32 v[0:1], s[4:5], v75, s4, v[0:1]
	v_lshlrev_b32_e32 v194, 4, v168
	v_lshl_add_u64 v[0:1], v[0:1], 0, v[194:195]
	global_load_dwordx4 v[144:147], v[0:1], off
	global_load_dwordx4 v[152:155], v[0:1], off offset:32
	global_load_dwordx4 v[148:151], v[0:1], off offset:64
	global_load_dwordx4 v[156:159], v[0:1], off offset:96
	global_load_dwordx4 v[140:143], v[0:1], off offset:128
	global_load_dwordx4 v[132:135], v[0:1], off offset:160
	global_load_dwordx4 v[136:139], v[0:1], off offset:192
	global_load_dwordx4 v[128:131], v[0:1], off offset:224
	s_lshl_b32 s4, s65, 6
	s_lshl_b32 s42, s65, 7
	s_and_b32 s4, s4, 0x100
	s_add_u32 s21, s57, s4
	s_addc_u32 s43, s58, 0
	s_add_u32 s44, s59, s4
	s_addc_u32 s45, s60, 0
	s_add_i32 s5, 0, 0x14000
	s_cmp_lg_u32 0, -1
	s_cselect_b32 s4, 0, 0
	s_add_i32 s38, s4, 0xc000
	v_lshlrev_b32_e32 v233, 4, v73
	s_movk_i32 s6, 0x70
	v_lshl_add_u32 v234, v161, 8, s38
	v_bitop3_b32 v0, v194, v233, s6 bitop3:0x78
	v_and_b32_e32 v170, 63, v73
	v_add_u32_e32 v176, v0, v234
	v_lshlrev_b32_e32 v0, 7, v169
	v_or_b32_e32 v0, v0, v170
	v_ashrrev_i32_e32 v1, 31, v0
	v_lshrrev_b32_e32 v1, 28, v1
	v_add_u32_e32 v1, v0, v1
	v_ashrrev_i32_e32 v2, 4, v1
	v_and_b32_e32 v1, -16, v1
	s_movk_i32 s6, 0xb00
	v_sub_u32_e32 v1, v0, v1
	v_mul_lo_u32 v3, v2, s6
	v_bitop3_b32 v2, v2, v1, 7 bitop3:0x6c
	v_lshl_add_u32 v162, v2, 3, v3
	v_bfe_i32 v2, v169, 24, 1
	v_lshrrev_b32_e32 v2, 28, v2
	v_add3_u32 v0, v2, v0, 64
	v_ashrrev_i32_e32 v0, 4, v0
	v_mul_lo_u32 v2, v0, s6
	v_bitop3_b32 v0, v0, v1, 7 bitop3:0x6c
	v_bfe_u32 v1, v73, 2, 3
	v_lshl_or_b32 v1, v169, 3, v1
	v_mul_lo_u32 v1, v1, s6
	s_mul_i32 s6, s20, 0xb00
	s_mov_b32 s7, s31
	v_lshlrev_b32_e32 v171, 3, v73
	s_lshl_b64 s[6:7], s[6:7], 1
	v_lshl_add_u32 v164, v0, 3, v2
	v_and_b32_e32 v0, 32, v73
	v_and_b32_e32 v2, 24, v171
	s_add_u32 s8, s21, s6
	v_ashrrev_i32_e32 v163, 31, v162
	v_or3_b32 v166, v0, v2, v1
	v_lshlrev_b32_e32 v179, 11, v169
	s_addc_u32 s9, s43, s7
	v_lshlrev_b64 v[0:1], 1, v[162:163]
	v_add_u32_e32 v180, s38, v179
	v_lshl_add_u64 v[2:3], s[8:9], 0, v[0:1]
	v_ashrrev_i32_e32 v165, 31, v164
	v_readfirstlane_b32 s39, v180
	s_mov_b32 s40, m0
	s_mov_b32 m0, s39
	s_nop 0
	global_load_lds_dwordx4 v[2:3], off
	s_mov_b32 m0, s40
	v_lshlrev_b64 v[2:3], 1, v[164:165]
	v_lshl_add_u64 v[4:5], s[8:9], 0, v[2:3]
	s_add_i32 s8, s39, 0x400
	s_mov_b32 s9, m0
	s_mov_b32 m0, s8
	s_nop 0
	global_load_lds_dwordx4 v[4:5], off
	s_mov_b32 m0, s9
	v_add_u32_e32 v4, s4, v179
	s_add_u32 s6, s44, s6
	v_ashrrev_i32_e32 v167, 31, v166
	v_readfirstlane_b32 s8, v4
	s_addc_u32 s7, s45, s7
	v_lshlrev_b64 v[4:5], 1, v[166:167]
	v_lshl_add_u64 v[6:7], s[6:7], 0, v[4:5]
	s_mov_b32 s6, m0
	s_mov_b32 m0, s8
	s_nop 0
	global_load_lds_dwordx4 v[6:7], off
	s_mov_b32 m0, s6
	s_add_i32 s6, s8, 0x400
	v_lshl_add_u64 v[6:7], v[6:7], 0, s[22:23]
	s_mov_b32 s7, m0
	s_mov_b32 m0, s6
	s_nop 0
	global_load_lds_dwordx4 v[6:7], off
	s_mov_b32 m0, s7
	v_readfirstlane_b32 s39, v179
	s_mul_i32 s6, s64, 0xb0000
	s_add_i32 s38, s38, s39
	s_add_i32 s6, s6, 0x2c2c000
	s_mov_b32 s7, s31
	s_add_i32 s40, s38, 0x4000
	s_lshl_b64 s[6:7], s[6:7], 1
	s_add_u32 s8, s21, s6
	s_addc_u32 s9, s43, s7
	v_lshl_add_u64 v[0:1], s[8:9], 0, v[0:1]
	s_mov_b32 s41, m0
	s_mov_b32 m0, s40
	s_nop 0
	global_load_lds_dwordx4 v[0:1], off
	s_mov_b32 m0, s41
	v_lshl_add_u64 v[0:1], s[8:9], 0, v[2:3]
	s_addk_i32 s38, 0x4400
	s_mov_b32 s8, m0
	s_mov_b32 m0, s38
	s_nop 0
	global_load_lds_dwordx4 v[0:1], off
	s_mov_b32 m0, s8
	s_add_i32 s4, s4, s39
	s_add_i32 s8, s4, 0x4000
	s_add_u32 s6, s44, s6
	s_addc_u32 s7, s45, s7
	v_lshl_add_u64 v[0:1], s[6:7], 0, v[4:5]
	s_mov_b32 s6, m0
	s_mov_b32 m0, s8
	s_nop 0
	global_load_lds_dwordx4 v[0:1], off
	s_mov_b32 m0, s6
	v_lshl_add_u64 v[0:1], v[0:1], 0, s[22:23]
	s_addk_i32 s4, 0x4400
	s_mov_b32 s6, m0
	s_mov_b32 m0, s4
	s_nop 0
	global_load_lds_dwordx4 v[0:1], off
	s_mov_b32 m0, s6
	s_andn2_b64 vcc, exec, s[18:19]
	s_cbranch_vccnz .LBB0_770
; template <int DQ, int MODE>
; __device__ __forceinline__ void attn_unit(const Args& a, char* lds, const int wave0) {
;     ...
;     if (a.qgain) { float xf[8][8]; float ss = 0.f;
; #pragma unroll
;       for (int d0 = 0; d0 < 8; ++d0)
; #pragma unroll
;         for (int e = 0; e < 8; ++e) { xf[d0][e] = __uint_as_float(((unsigned)(unsigned short)qr[d0][e]) << 16); ss += xf[d0][e] * xf[d0][e]; }
	s_waitcnt vmcnt(15)
	v_and_b32_e32 v71, 0xffff0000, v144
	v_lshlrev_b32_e32 v70, 16, v144
	v_mul_f32_e32 v84, v71, v71
	v_and_b32_e32 v57, 0xffff0000, v145
	v_lshlrev_b32_e32 v56, 16, v145
	v_pk_fma_f32 v[84:85], v[70:71], v[70:71], v[84:85] op_sel_hi:[1,1,0]
	v_mul_f32_e32 v86, v57, v57
	v_pk_fma_f32 v[84:85], v[56:57], v[56:57], v[84:85]
	v_and_b32_e32 v101, 0xffff0000, v146
	v_lshlrev_b32_e32 v100, 16, v146
	v_pk_add_f32 v[84:85], v[86:87], v[84:85] op_sel_hi:[0,1]
	v_pk_fma_f32 v[84:85], v[100:101], v[100:101], v[84:85]
	v_mul_f32_e32 v86, v101, v101
	v_and_b32_e32 v65, 0xffff0000, v147
	v_lshlrev_b32_e32 v64, 16, v147
	v_pk_add_f32 v[84:85], v[86:87], v[84:85] op_sel_hi:[0,1]
	v_pk_fma_f32 v[84:85], v[64:65], v[64:65], v[84:85]
	v_mul_f32_e32 v86, v65, v65
	s_waitcnt vmcnt(14)
	v_and_b32_e32 v59, 0xffff0000, v152
	v_lshlrev_b32_e32 v58, 16, v152
	v_pk_add_f32 v[84:85], v[86:87], v[84:85] op_sel_hi:[0,1]
	v_pk_fma_f32 v[84:85], v[58:59], v[58:59], v[84:85]
	v_mul_f32_e32 v86, v59, v59
	v_and_b32_e32 v55, 0xffff0000, v153
	v_lshlrev_b32_e32 v54, 16, v153
	v_pk_add_f32 v[84:85], v[86:87], v[84:85] op_sel_hi:[0,1]
	v_pk_fma_f32 v[84:85], v[54:55], v[54:55], v[84:85]
	v_mul_f32_e32 v86, v55, v55
	v_and_b32_e32 v51, 0xffff0000, v154
	v_lshlrev_b32_e32 v50, 16, v154
	v_pk_add_f32 v[84:85], v[86:87], v[84:85] op_sel_hi:[0,1]
	v_pk_fma_f32 v[84:85], v[50:51], v[50:51], v[84:85]
	v_mul_f32_e32 v86, v51, v51
	v_and_b32_e32 v37, 0xffff0000, v155
	v_lshlrev_b32_e32 v36, 16, v155
	v_pk_add_f32 v[84:85], v[86:87], v[84:85] op_sel_hi:[0,1]
	v_pk_fma_f32 v[84:85], v[36:37], v[36:37], v[84:85]
	v_mul_f32_e32 v86, v37, v37
	s_waitcnt vmcnt(13)
	v_and_b32_e32 v107, 0xffff0000, v148
	v_lshlrev_b32_e32 v106, 16, v148
	v_pk_add_f32 v[84:85], v[86:87], v[84:85] op_sel_hi:[0,1]
	v_pk_fma_f32 v[84:85], v[106:107], v[106:107], v[84:85]
	v_mul_f32_e32 v86, v107, v107
	v_and_b32_e32 v105, 0xffff0000, v149
	v_lshlrev_b32_e32 v104, 16, v149
	v_pk_add_f32 v[84:85], v[86:87], v[84:85] op_sel_hi:[0,1]
	v_pk_fma_f32 v[84:85], v[104:105], v[104:105], v[84:85]
	v_mul_f32_e32 v86, v105, v105
	v_and_b32_e32 v103, 0xffff0000, v150
	v_lshlrev_b32_e32 v102, 16, v150
	v_pk_add_f32 v[84:85], v[86:87], v[84:85] op_sel_hi:[0,1]
	v_pk_fma_f32 v[84:85], v[102:103], v[102:103], v[84:85]
	v_mul_f32_e32 v86, v103, v103
	v_and_b32_e32 v69, 0xffff0000, v151
	v_lshlrev_b32_e32 v68, 16, v151
	v_pk_add_f32 v[84:85], v[86:87], v[84:85] op_sel_hi:[0,1]
	v_pk_fma_f32 v[84:85], v[68:69], v[68:69], v[84:85]
	v_mul_f32_e32 v86, v69, v69
	v_lshlrev_b32_e32 v74, 3, v168
	s_waitcnt vmcnt(12)
	v_and_b32_e32 v67, 0xffff0000, v156
	v_lshlrev_b32_e32 v66, 16, v156
	v_pk_add_f32 v[84:85], v[86:87], v[84:85] op_sel_hi:[0,1]
	v_lshlrev_b32_e32 v96, 2, v74
	v_pk_fma_f32 v[84:85], v[66:67], v[66:67], v[84:85]
	v_mul_f32_e32 v86, v67, v67
	global_load_dwordx4 v[4:7], v96, s[16:17] offset:272
	global_load_dwordx4 v[12:15], v96, s[16:17] offset:256
	global_load_dwordx4 v[0:3], v96, s[16:17] offset:400
	global_load_dwordx4 v[8:11], v96, s[16:17] offset:384
	global_load_dwordx4 v[24:27], v96, s[16:17] offset:80
	global_load_dwordx4 v[28:31], v96, s[16:17] offset:64
	global_load_dwordx4 v[16:19], v96, s[16:17] offset:208
	global_load_dwordx4 v[20:23], v96, s[16:17] offset:192
	v_and_b32_e32 v47, 0xffff0000, v157
	v_lshlrev_b32_e32 v46, 16, v157
	v_pk_add_f32 v[84:85], v[86:87], v[84:85] op_sel_hi:[0,1]
	global_load_dwordx4 v[60:63], v96, s[16:17] offset:16
	global_load_dwordx4 v[76:79], v96, s[16:17]
	global_load_dwordx4 v[32:35], v96, s[16:17] offset:144
	global_load_dwordx4 v[80:83], v96, s[16:17] offset:128
	v_pk_fma_f32 v[84:85], v[46:47], v[46:47], v[84:85]
	v_mul_f32_e32 v86, v47, v47
	v_and_b32_e32 v45, 0xffff0000, v158
	v_lshlrev_b32_e32 v44, 16, v158
	v_pk_add_f32 v[84:85], v[86:87], v[84:85] op_sel_hi:[0,1]
	v_pk_fma_f32 v[84:85], v[44:45], v[44:45], v[84:85]
	v_mul_f32_e32 v86, v45, v45
	v_and_b32_e32 v43, 0xffff0000, v159
	v_lshlrev_b32_e32 v42, 16, v159
	v_pk_add_f32 v[84:85], v[86:87], v[84:85] op_sel_hi:[0,1]
	v_pk_fma_f32 v[84:85], v[42:43], v[42:43], v[84:85]
	v_mul_f32_e32 v86, v43, v43
	s_waitcnt vmcnt(23)
	v_and_b32_e32 v41, 0xffff0000, v140
	v_lshlrev_b32_e32 v40, 16, v140
	v_pk_add_f32 v[84:85], v[86:87], v[84:85] op_sel_hi:[0,1]
	v_pk_fma_f32 v[84:85], v[40:41], v[40:41], v[84:85]
	v_mul_f32_e32 v86, v41, v41
	v_and_b32_e32 v39, 0xffff0000, v141
	v_lshlrev_b32_e32 v38, 16, v141
	v_pk_add_f32 v[84:85], v[86:87], v[84:85] op_sel_hi:[0,1]
	v_pk_fma_f32 v[84:85], v[38:39], v[38:39], v[84:85]
	v_mul_f32_e32 v86, v39, v39
	v_pk_add_f32 v[84:85], v[86:87], v[84:85] op_sel_hi:[0,1]
	v_and_b32_e32 v109, 0xffff0000, v142
	v_lshlrev_b32_e32 v108, 16, v142
	v_pk_fma_f32 v[84:85], v[108:109], v[108:109], v[84:85]
	v_mul_f32_e32 v86, v109, v109
	v_pk_add_f32 v[84:85], v[86:87], v[84:85] op_sel_hi:[0,1]
	v_and_b32_e32 v113, 0xffff0000, v143
	v_lshlrev_b32_e32 v112, 16, v143
	v_pk_fma_f32 v[84:85], v[112:113], v[112:113], v[84:85]
	v_mul_f32_e32 v86, v113, v113
	v_pk_add_f32 v[92:93], v[86:87], v[84:85] op_sel_hi:[0,1]
	global_load_dwordx4 v[84:87], v96, s[16:17] offset:336
	global_load_dwordx4 v[88:91], v96, s[16:17] offset:320
	s_waitcnt vmcnt(24)
	v_and_b32_e32 v117, 0xffff0000, v132
	v_lshlrev_b32_e32 v116, 16, v132
	v_pk_fma_f32 v[92:93], v[116:117], v[116:117], v[92:93]
	v_mul_f32_e32 v94, v117, v117
	v_pk_add_f32 v[120:121], v[94:95], v[92:93] op_sel_hi:[0,1]
	global_load_dwordx4 v[92:95], v96, s[16:17] offset:464
	s_nop 0
	global_load_dwordx4 v[96:99], v96, s[16:17] offset:448
	v_and_b32_e32 v123, 0xffff0000, v133
	v_lshlrev_b32_e32 v122, 16, v133
	v_pk_fma_f32 v[120:121], v[122:123], v[122:123], v[120:121]
	v_mul_f32_e32 v126, v123, v123
	v_pk_add_f32 v[120:121], v[126:127], v[120:121] op_sel_hi:[0,1]
	v_and_b32_e32 v127, 0xffff0000, v134
	v_lshlrev_b32_e32 v126, 16, v134
	s_waitcnt vmcnt(24)
; template <int DQ, int MODE>
; __device__ __forceinline__ void attn_unit(const Args& a, char* lds, const int wave0) {
;     ...
;         for (int e = 0; e < 8; ++e) { xf[d0][e] = __uint_as_float(((unsigned)(unsigned short)qr[d0][e]) << 16); ss += xf[d0][e] * xf[d0][e]; }
;       { auto rr = __builtin_amdgcn_permlane32_swap(__float_as_uint(ss), __float_as_uint(ss), false, false); ss = __uint_as_float(rr[0]) + __uint_as_float(rr[1]); }
;       const float rstd = rsqrtf(ss * (1.0f / 128.0f) + 1e-6f) * a.C;
; #pragma unroll
;       for (int d0 = 0; d0 < 8; ++d0) { const float* gp = a.qgain + d0 * 16 + hi * 8;
; #pragma unroll
;         for (int e = 0; e < 8; ++e) xf[d0][e] = xf[d0][e] * rstd * gp[e]; }
;       if (a.qrope_t0 >= 0) { const int t = a.qrope_t0 + wid * QBLK + r32; const float prow = (float)(t >> 6), pcol = (float)(t & 63);
	v_and_b32_e32 v119, 0xffff0000, v128
	v_lshlrev_b32_e32 v118, 16, v128
	v_and_b32_e32 v125, 0xffff0000, v129
	v_lshlrev_b32_e32 v124, 16, v129
	v_and_b32_e32 v129, 0xffff0000, v130
	v_lshlrev_b32_e32 v128, 16, v130
	v_pk_fma_f32 v[120:121], v[126:127], v[126:127], v[120:121]
	v_mul_f32_e32 v130, v127, v127
	v_pk_add_f32 v[120:121], v[130:131], v[120:121] op_sel_hi:[0,1]
	v_and_b32_e32 v133, 0xffff0000, v135
	v_lshlrev_b32_e32 v132, 16, v135
	v_pk_fma_f32 v[120:121], v[132:133], v[132:133], v[120:121]
	v_mul_f32_e32 v130, v133, v133
	v_and_b32_e32 v53, 0xffff0000, v136
	v_lshlrev_b32_e32 v52, 16, v136
	v_pk_add_f32 v[120:121], v[130:131], v[120:121] op_sel_hi:[0,1]
	v_pk_fma_f32 v[120:121], v[52:53], v[52:53], v[120:121]
	v_mul_f32_e32 v130, v53, v53
	v_and_b32_e32 v49, 0xffff0000, v137
	v_lshlrev_b32_e32 v48, 16, v137
	v_pk_add_f32 v[120:121], v[130:131], v[120:121] op_sel_hi:[0,1]
	v_pk_fma_f32 v[120:121], v[48:49], v[48:49], v[120:121]
	v_mul_f32_e32 v130, v49, v49
	v_and_b32_e32 v111, 0xffff0000, v138
	v_lshlrev_b32_e32 v110, 16, v138
	v_pk_add_f32 v[120:121], v[130:131], v[120:121] op_sel_hi:[0,1]
	v_pk_fma_f32 v[120:121], v[110:111], v[110:111], v[120:121]
	v_mul_f32_e32 v130, v111, v111
	v_and_b32_e32 v115, 0xffff0000, v139
	v_lshlrev_b32_e32 v114, 16, v139
	v_pk_add_f32 v[120:121], v[130:131], v[120:121] op_sel_hi:[0,1]
	v_pk_fma_f32 v[120:121], v[114:115], v[114:115], v[120:121]
	v_mul_f32_e32 v130, v115, v115
	v_pk_add_f32 v[120:121], v[130:131], v[120:121] op_sel_hi:[0,1]
	v_pk_fma_f32 v[120:121], v[118:119], v[118:119], v[120:121]
	v_mul_f32_e32 v130, v119, v119
	v_pk_add_f32 v[120:121], v[130:131], v[120:121] op_sel_hi:[0,1]
	v_pk_fma_f32 v[120:121], v[124:125], v[124:125], v[120:121]
	v_mul_f32_e32 v130, v125, v125
	v_pk_add_f32 v[120:121], v[130:131], v[120:121] op_sel_hi:[0,1]
	v_pk_fma_f32 v[120:121], v[128:129], v[128:129], v[120:121]
	v_mul_f32_e32 v130, v129, v129
	v_and_b32_e32 v135, 0xffff0000, v131
	v_lshlrev_b32_e32 v134, 16, v131
	v_pk_add_f32 v[120:121], v[130:131], v[120:121] op_sel_hi:[0,1]
	v_pk_fma_f32 v[120:121], v[134:135], v[134:135], v[120:121]
	v_mul_f32_e32 v130, v135, v135
	v_pk_add_f32 v[120:121], v[130:131], v[120:121] op_sel_hi:[0,1]
	v_mov_b32_e32 v121, v120
	s_nop 1
	v_permlane32_swap_b32_e32 v120, v121
	v_add_f32_e32 v120, v120, v121
	v_fmamk_f32 v120, v120, 0x3c000000, v196
	v_mul_f32_e32 v121, 0x4b800000, v120
	v_cmp_gt_f32_e32 vcc, s78, v120
	s_cmp_lt_i32 s66, 0
	s_nop 0
	v_cndmask_b32_e32 v120, v120, v121, vcc
	v_rsq_f32_e32 v120, v120
	s_nop 0
	v_mul_f32_e32 v121, 0x45800000, v120
	v_cndmask_b32_e32 v120, v120, v121, vcc
	v_mul_f32_e32 v120, 0x3e0293ee, v120
	v_pk_mul_f32 v[64:65], v[120:121], v[64:65] op_sel_hi:[0,1]
	v_pk_mul_f32 v[58:59], v[120:121], v[58:59] op_sel_hi:[0,1]
	s_waitcnt vmcnt(7)
	v_pk_mul_f32 v[64:65], v[62:63], v[64:65]
	v_pk_mul_f32 v[62:63], v[28:29], v[58:59]
	v_pk_mul_f32 v[28:29], v[120:121], v[54:55] op_sel_hi:[0,1]
	v_pk_mul_f32 v[58:59], v[28:29], v[30:31]
	v_pk_mul_f32 v[28:29], v[120:121], v[50:51] op_sel_hi:[0,1]
	v_pk_mul_f32 v[54:55], v[28:29], v[24:25]
	v_pk_mul_f32 v[24:25], v[120:121], v[36:37] op_sel_hi:[0,1]
	v_pk_mul_f32 v[50:51], v[24:25], v[26:27]
	v_pk_mul_f32 v[24:25], v[120:121], v[106:107] op_sel_hi:[0,1]
	s_waitcnt vmcnt(4)
	v_pk_mul_f32 v[36:37], v[24:25], v[80:81]
	v_pk_mul_f32 v[24:25], v[120:121], v[104:105] op_sel_hi:[0,1]
	v_pk_mul_f32 v[30:31], v[24:25], v[82:83]
	v_pk_mul_f32 v[24:25], v[120:121], v[102:103] op_sel_hi:[0,1]
	v_pk_mul_f32 v[28:29], v[24:25], v[32:33]
	v_pk_mul_f32 v[24:25], v[120:121], v[68:69] op_sel_hi:[0,1]
	v_pk_mul_f32 v[26:27], v[24:25], v[34:35]
	v_pk_mul_f32 v[24:25], v[120:121], v[66:67] op_sel_hi:[0,1]
	v_pk_mul_f32 v[24:25], v[24:25], v[20:21]
	v_pk_mul_f32 v[20:21], v[120:121], v[46:47] op_sel_hi:[0,1]
	v_pk_mul_f32 v[22:23], v[20:21], v[22:23]
	v_pk_mul_f32 v[20:21], v[120:121], v[44:45] op_sel_hi:[0,1]
	v_pk_mul_f32 v[20:21], v[20:21], v[16:17]
	v_pk_mul_f32 v[16:17], v[120:121], v[42:43] op_sel_hi:[0,1]
	v_pk_mul_f32 v[18:19], v[16:17], v[18:19]
	v_pk_mul_f32 v[16:17], v[120:121], v[40:41] op_sel_hi:[0,1]
	v_pk_mul_f32 v[46:47], v[16:17], v[12:13]
	v_pk_mul_f32 v[12:13], v[120:121], v[38:39] op_sel_hi:[0,1]
	v_pk_mul_f32 v[44:45], v[12:13], v[14:15]
	v_pk_mul_f32 v[12:13], v[120:121], v[108:109] op_sel_hi:[0,1]
	v_pk_mul_f32 v[42:43], v[12:13], v[4:5]
	v_pk_mul_f32 v[4:5], v[120:121], v[112:113] op_sel_hi:[0,1]
	v_pk_mul_f32 v[40:41], v[4:5], v[6:7]
	v_pk_mul_f32 v[4:5], v[120:121], v[116:117] op_sel_hi:[0,1]
	s_waitcnt vmcnt(2)
	v_pk_mul_f32 v[38:39], v[4:5], v[88:89]
	v_pk_mul_f32 v[4:5], v[120:121], v[122:123] op_sel_hi:[0,1]
	v_pk_mul_f32 v[34:35], v[4:5], v[90:91]
	v_pk_mul_f32 v[4:5], v[120:121], v[126:127] op_sel_hi:[0,1]
	v_pk_mul_f32 v[32:33], v[4:5], v[84:85]
	v_pk_mul_f32 v[4:5], v[120:121], v[132:133] op_sel_hi:[0,1]
	v_pk_mul_f32 v[16:17], v[4:5], v[86:87]
	v_pk_mul_f32 v[4:5], v[120:121], v[52:53] op_sel_hi:[0,1]
	v_pk_mul_f32 v[12:13], v[4:5], v[8:9]
	v_pk_mul_f32 v[4:5], v[120:121], v[48:49] op_sel_hi:[0,1]
	v_pk_mul_f32 v[8:9], v[4:5], v[10:11]
	v_pk_mul_f32 v[4:5], v[120:121], v[110:111] op_sel_hi:[0,1]
	v_pk_mul_f32 v[70:71], v[120:121], v[70:71] op_sel_hi:[0,1]
	v_pk_mul_f32 v[10:11], v[4:5], v[0:1]
	v_pk_mul_f32 v[0:1], v[120:121], v[114:115] op_sel_hi:[0,1]
	v_pk_mul_f32 v[70:71], v[76:77], v[70:71]
	v_pk_mul_f32 v[56:57], v[120:121], v[56:57] op_sel_hi:[0,1]
	v_pk_mul_f32 v[76:77], v[120:121], v[100:101] op_sel_hi:[0,1]
	v_pk_mul_f32 v[14:15], v[0:1], v[2:3]
	v_pk_mul_f32 v[0:1], v[120:121], v[118:119] op_sel_hi:[0,1]
	v_pk_mul_f32 v[2:3], v[120:121], v[124:125] op_sel_hi:[0,1]
	v_pk_mul_f32 v[4:5], v[120:121], v[128:129] op_sel_hi:[0,1]
	v_pk_mul_f32 v[6:7], v[120:121], v[134:135] op_sel_hi:[0,1]
	v_pk_mul_f32 v[56:57], v[78:79], v[56:57]
	v_pk_mul_f32 v[60:61], v[60:61], v[76:77]
	s_waitcnt vmcnt(0)
	v_pk_mul_f32 v[0:1], v[0:1], v[96:97]
	v_pk_mul_f32 v[2:3], v[2:3], v[98:99]
	v_pk_mul_f32 v[4:5], v[4:5], v[92:93]
	v_pk_mul_f32 v[6:7], v[6:7], v[94:95]
	s_cbranch_scc1 .LBB0_769
; template <int DQ, int MODE>
; __device__ __forceinline__ void attn_unit(const Args& a, char* lds, const int wave0) {
;     ...
;       if (a.qrope_t0 >= 0) { const int t = a.qrope_t0 + wid * QBLK + r32; const float prow = (float)(t >> 6), pcol = (float)(t & 63);
; #pragma unroll
;         for (int half = 0; half < 2; ++half)
; #pragma unroll
;           for (int blk = 0; blk < 2; ++blk)
; #pragma unroll
;             for (int e = 0; e < 8; ++e) { const int j = blk * 16 + hi * 8 + e, da = 4 * half + blk, db = da + 2;
;               const float inv_freq = __builtin_amdgcn_exp2f(-(float)j * (13.287712379549449f / 32.0f)); float rev = (half ? pcol : prow) * inv_freq * 0.15915494309189535f; rev -= rintf(rev);
;               const float sn = __builtin_amdgcn_sinf(rev), cs = __builtin_amdgcn_cosf(rev);
;               const float x = xf[da][e], y = xf[db][e]; xf[da][e] = x * cs - y * sn; xf[db][e] = y * cs + x * sn; } }
	v_add_u32_e32 v48, s66, v75
	v_ashrrev_i32_e32 v49, 6, v48
	v_and_b32_e32 v48, 63, v48
	v_cvt_f32_ubyte0_e32 v66, v48
	v_or_b32_e32 v48, 16, v74
	v_cvt_f32_ubyte0_e32 v48, v48
	v_mul_f32_e32 v48, 0xbed49a78, v48
	v_exp_f32_e32 v67, v48
	v_cvt_f32_ubyte0_e32 v48, v74
	v_mul_f32_e32 v48, 0xbed49a78, v48
	v_cvt_f32_i32_e32 v69, v49
	v_exp_f32_e32 v68, v48
	s_nop 0
	v_mul_f32_e32 v48, v68, v69
	v_mul_f32_e32 v49, 0.15915494, v48
	v_rndne_f32_e32 v49, v49
	v_fma_f32 v48, v48, 0.15915494, -v49
	v_sin_f32_e32 v52, v48
	v_cos_f32_e32 v76, v48
	v_or_b32_e32 v48, 1, v74
	v_cvt_f32_ubyte0_e32 v48, v48
	v_mul_f32_e32 v48, 0xbed49a78, v48
	v_exp_f32_e32 v75, v48
	s_nop 0
	v_mul_f32_e32 v48, v75, v69
	v_mul_f32_e32 v49, 0.15915494, v48
	v_rndne_f32_e32 v49, v49
	v_fma_f32 v48, v48, 0.15915494, -v49
	v_sin_f32_e32 v53, v48
	v_cos_f32_e32 v77, v48
	v_pk_mul_f32 v[48:49], v[52:53], v[36:37]
	v_pk_mul_f32 v[36:37], v[76:77], v[36:37]
	v_pk_fma_f32 v[48:49], v[76:77], v[70:71], v[48:49] neg_lo:[0,0,1] neg_hi:[0,0,1]
	v_pk_fma_f32 v[36:37], v[52:53], v[70:71], v[36:37]
	v_or_b32_e32 v52, 2, v74
	v_cvt_f32_ubyte0_e32 v52, v52
	v_mul_f32_e32 v52, 0xbed49a78, v52
	v_exp_f32_e32 v70, v52
	s_nop 0
	v_mul_f32_e32 v52, v70, v69
	v_mul_f32_e32 v53, 0.15915494, v52
	v_rndne_f32_e32 v53, v53
	v_fma_f32 v52, v52, 0.15915494, -v53
	v_sin_f32_e32 v76, v52
	v_cos_f32_e32 v78, v52
	v_or_b32_e32 v52, 3, v74
	v_cvt_f32_ubyte0_e32 v52, v52
	v_mul_f32_e32 v52, 0xbed49a78, v52
	v_exp_f32_e32 v71, v52
	s_nop 0
	v_mul_f32_e32 v52, v71, v69
	v_mul_f32_e32 v53, 0.15915494, v52
	v_rndne_f32_e32 v53, v53
	v_fma_f32 v52, v52, 0.15915494, -v53
	v_sin_f32_e32 v77, v52
	v_cos_f32_e32 v79, v52
	v_pk_mul_f32 v[52:53], v[76:77], v[30:31]
	v_pk_mul_f32 v[30:31], v[78:79], v[30:31]
	v_pk_fma_f32 v[52:53], v[78:79], v[56:57], v[52:53] neg_lo:[0,0,1] neg_hi:[0,0,1]
	v_pk_fma_f32 v[30:31], v[76:77], v[56:57], v[30:31]
	v_or_b32_e32 v56, 4, v74
	v_cvt_f32_ubyte0_e32 v56, v56
	v_mul_f32_e32 v56, 0xbed49a78, v56
	v_exp_f32_e32 v76, v56
	s_nop 0
	v_mul_f32_e32 v56, v76, v69
	v_mul_f32_e32 v57, 0.15915494, v56
	v_rndne_f32_e32 v57, v57
	v_fma_f32 v56, v56, 0.15915494, -v57
	v_sin_f32_e32 v78, v56
	v_cos_f32_e32 v80, v56
	v_or_b32_e32 v56, 5, v74
	v_cvt_f32_ubyte0_e32 v56, v56
	v_mul_f32_e32 v56, 0xbed49a78, v56
	v_exp_f32_e32 v77, v56
	s_nop 0
	v_mul_f32_e32 v56, v77, v69
	v_mul_f32_e32 v57, 0.15915494, v56
	v_rndne_f32_e32 v57, v57
	v_fma_f32 v56, v56, 0.15915494, -v57
	v_sin_f32_e32 v79, v56
	v_cos_f32_e32 v81, v56
	v_pk_mul_f32 v[56:57], v[78:79], v[28:29]
	v_pk_mul_f32 v[28:29], v[80:81], v[28:29]
	v_pk_fma_f32 v[56:57], v[80:81], v[60:61], v[56:57] neg_lo:[0,0,1] neg_hi:[0,0,1]
	v_pk_fma_f32 v[28:29], v[78:79], v[60:61], v[28:29]
	v_or_b32_e32 v60, 6, v74
	v_cvt_f32_ubyte0_e32 v60, v60
	v_mul_f32_e32 v60, 0xbed49a78, v60
	v_exp_f32_e32 v82, v60
	s_nop 0
	v_mul_f32_e32 v60, v82, v69
	v_mul_f32_e32 v61, 0.15915494, v60
	v_rndne_f32_e32 v61, v61
	v_fma_f32 v60, v60, 0.15915494, -v61
	v_sin_f32_e32 v78, v60
	v_cos_f32_e32 v80, v60
	v_or_b32_e32 v60, 7, v74
	v_cvt_f32_ubyte0_e32 v60, v60
	v_mul_f32_e32 v60, 0xbed49a78, v60
	v_exp_f32_e32 v83, v60
	s_nop 0
	v_mul_f32_e32 v60, v83, v69
	v_mul_f32_e32 v61, 0.15915494, v60
	v_rndne_f32_e32 v61, v61
	v_fma_f32 v60, v60, 0.15915494, -v61
	v_sin_f32_e32 v79, v60
	v_cos_f32_e32 v81, v60
	v_pk_mul_f32 v[60:61], v[78:79], v[26:27]
	v_pk_mul_f32 v[26:27], v[80:81], v[26:27]
	v_pk_fma_f32 v[60:61], v[80:81], v[64:65], v[60:61] neg_lo:[0,0,1] neg_hi:[0,0,1]
	v_pk_fma_f32 v[26:27], v[78:79], v[64:65], v[26:27]
	v_mul_f32_e32 v64, v67, v69
	v_mul_f32_e32 v65, 0.15915494, v64
	v_rndne_f32_e32 v65, v65
	v_fma_f32 v64, v64, 0.15915494, -v65
	v_sin_f32_e32 v78, v64
	v_cos_f32_e32 v80, v64
	v_or_b32_e32 v64, 17, v74
	v_cvt_f32_ubyte0_e32 v64, v64
	v_mul_f32_e32 v64, 0xbed49a78, v64
	v_exp_f32_e32 v84, v64
	s_nop 0
	v_mul_f32_e32 v64, v84, v69
	v_mul_f32_e32 v65, 0.15915494, v64
	v_rndne_f32_e32 v65, v65
	v_fma_f32 v64, v64, 0.15915494, -v65
	v_sin_f32_e32 v79, v64
	v_cos_f32_e32 v81, v64
	v_pk_mul_f32 v[64:65], v[78:79], v[24:25]
	v_pk_mul_f32 v[24:25], v[80:81], v[24:25]
	v_pk_fma_f32 v[64:65], v[80:81], v[62:63], v[64:65] neg_lo:[0,0,1] neg_hi:[0,0,1]
	v_pk_fma_f32 v[24:25], v[78:79], v[62:63], v[24:25]
	v_or_b32_e32 v62, 18, v74
	v_cvt_f32_ubyte0_e32 v62, v62
	v_mul_f32_e32 v62, 0xbed49a78, v62
	v_exp_f32_e32 v85, v62
	s_nop 0
	v_mul_f32_e32 v62, v85, v69
	v_mul_f32_e32 v63, 0.15915494, v62
	v_rndne_f32_e32 v63, v63
	v_fma_f32 v62, v62, 0.15915494, -v63
	v_sin_f32_e32 v78, v62
	v_cos_f32_e32 v80, v62
	v_or_b32_e32 v62, 19, v74
	v_cvt_f32_ubyte0_e32 v62, v62
	v_mul_f32_e32 v62, 0xbed49a78, v62
	v_exp_f32_e32 v86, v62
	s_nop 0
	v_mul_f32_e32 v62, v86, v69
	v_mul_f32_e32 v63, 0.15915494, v62
	v_rndne_f32_e32 v63, v63
	v_fma_f32 v62, v62, 0.15915494, -v63
	v_sin_f32_e32 v79, v62
	v_cos_f32_e32 v81, v62
	v_pk_mul_f32 v[62:63], v[78:79], v[22:23]
	v_pk_mul_f32 v[22:23], v[80:81], v[22:23]
	v_pk_fma_f32 v[62:63], v[80:81], v[58:59], v[62:63] neg_lo:[0,0,1] neg_hi:[0,0,1]
	v_pk_fma_f32 v[22:23], v[78:79], v[58:59], v[22:23]
	v_or_b32_e32 v58, 20, v74
	v_cvt_f32_ubyte0_e32 v58, v58
	v_mul_f32_e32 v58, 0xbed49a78, v58
	v_exp_f32_e32 v87, v58
	s_nop 0
	v_mul_f32_e32 v58, v87, v69
	v_mul_f32_e32 v59, 0.15915494, v58
	v_rndne_f32_e32 v59, v59
	v_fma_f32 v58, v58, 0.15915494, -v59
	v_sin_f32_e32 v78, v58
	v_cos_f32_e32 v80, v58
	v_or_b32_e32 v58, 21, v74
	v_cvt_f32_ubyte0_e32 v58, v58
	v_mul_f32_e32 v58, 0xbed49a78, v58
	v_exp_f32_e32 v88, v58
	s_nop 0
	v_mul_f32_e32 v58, v88, v69
	v_mul_f32_e32 v59, 0.15915494, v58
	v_rndne_f32_e32 v59, v59
	v_fma_f32 v58, v58, 0.15915494, -v59
; template <int DQ, int MODE>
; __device__ __forceinline__ void attn_unit(const Args& a, char* lds, const int wave0) {
;     ...
;       if (a.qrope_t0 >= 0) { const int t = a.qrope_t0 + wid * QBLK + r32; const float prow = (float)(t >> 6), pcol = (float)(t & 63);
; #pragma unroll
;         for (int half = 0; half < 2; ++half)
; #pragma unroll
;           for (int blk = 0; blk < 2; ++blk)
; #pragma unroll
;             for (int e = 0; e < 8; ++e) { const int j = blk * 16 + hi * 8 + e, da = 4 * half + blk, db = da + 2;
;               const float inv_freq = __builtin_amdgcn_exp2f(-(float)j * (13.287712379549449f / 32.0f)); float rev = (half ? pcol : prow) * inv_freq * 0.15915494309189535f; rev -= rintf(rev);
;               const float sn = __builtin_amdgcn_sinf(rev), cs = __builtin_amdgcn_cosf(rev);
;               const float x = xf[da][e], y = xf[db][e]; xf[da][e] = x * cs - y * sn; xf[db][e] = y * cs + x * sn; } }
	v_sin_f32_e32 v79, v58
	v_cos_f32_e32 v81, v58
	v_pk_mul_f32 v[58:59], v[78:79], v[20:21]
	v_pk_mul_f32 v[20:21], v[80:81], v[20:21]
	v_pk_fma_f32 v[58:59], v[80:81], v[54:55], v[58:59] neg_lo:[0,0,1] neg_hi:[0,0,1]
	v_pk_fma_f32 v[20:21], v[78:79], v[54:55], v[20:21]
	v_or_b32_e32 v54, 22, v74
	v_cvt_f32_ubyte0_e32 v54, v54
	v_mul_f32_e32 v54, 0xbed49a78, v54
	v_exp_f32_e32 v89, v54
	s_nop 0
	v_mul_f32_e32 v54, v89, v69
	v_mul_f32_e32 v55, 0.15915494, v54
	v_rndne_f32_e32 v55, v55
	v_fma_f32 v54, v54, 0.15915494, -v55
	v_sin_f32_e32 v78, v54
	v_cos_f32_e32 v80, v54
	v_or_b32_e32 v54, 23, v74
	v_cvt_f32_ubyte0_e32 v54, v54
	v_mul_f32_e32 v54, 0xbed49a78, v54
	v_exp_f32_e32 v90, v54
	s_nop 0
	v_mul_f32_e32 v54, v90, v69
	v_mul_f32_e32 v55, 0.15915494, v54
	v_rndne_f32_e32 v55, v55
	v_fma_f32 v54, v54, 0.15915494, -v55
	v_sin_f32_e32 v79, v54
	v_cos_f32_e32 v81, v54
	v_pk_mul_f32 v[54:55], v[78:79], v[18:19]
	v_pk_mul_f32 v[18:19], v[80:81], v[18:19]
	v_pk_fma_f32 v[54:55], v[80:81], v[50:51], v[54:55] neg_lo:[0,0,1] neg_hi:[0,0,1]
	v_pk_fma_f32 v[18:19], v[78:79], v[50:51], v[18:19]
	v_mul_f32_e32 v50, v68, v66
	v_mul_f32_e32 v51, 0.15915494, v50
	v_rndne_f32_e32 v51, v51
	v_fma_f32 v50, v50, 0.15915494, -v51
	v_sin_f32_e32 v68, v50
	v_cos_f32_e32 v74, v50
	v_mul_f32_e32 v50, v75, v66
	v_mul_f32_e32 v51, 0.15915494, v50
	v_rndne_f32_e32 v51, v51
	v_fma_f32 v50, v50, 0.15915494, -v51
	v_sin_f32_e32 v69, v50
	v_cos_f32_e32 v75, v50
	v_pk_mul_f32 v[50:51], v[68:69], v[12:13]
	v_pk_mul_f32 v[12:13], v[74:75], v[12:13]
	v_pk_fma_f32 v[50:51], v[74:75], v[46:47], v[50:51] neg_lo:[0,0,1] neg_hi:[0,0,1]
	v_pk_fma_f32 v[12:13], v[68:69], v[46:47], v[12:13]
	v_mul_f32_e32 v46, v70, v66
	v_mul_f32_e32 v47, 0.15915494, v46
	v_rndne_f32_e32 v47, v47
	v_fma_f32 v47, v46, 0.15915494, -v47
	v_sin_f32_e32 v46, v47
	v_cos_f32_e32 v68, v47
	v_mul_f32_e32 v47, v71, v66
	v_mul_f32_e32 v69, 0.15915494, v47
	v_rndne_f32_e32 v69, v69
	v_fma_f32 v69, v47, 0.15915494, -v69
	v_sin_f32_e32 v47, v69
	v_cos_f32_e32 v69, v69
	v_pk_mul_f32 v[70:71], v[46:47], v[8:9]
	v_pk_mul_f32 v[8:9], v[68:69], v[8:9]
	v_pk_fma_f32 v[70:71], v[68:69], v[44:45], v[70:71] neg_lo:[0,0,1] neg_hi:[0,0,1]
	v_pk_fma_f32 v[8:9], v[46:47], v[44:45], v[8:9]
	v_mul_f32_e32 v44, v76, v66
	v_mul_f32_e32 v45, 0.15915494, v44
	v_rndne_f32_e32 v45, v45
	v_fma_f32 v45, v44, 0.15915494, -v45
	v_sin_f32_e32 v44, v45
	v_cos_f32_e32 v46, v45
	v_mul_f32_e32 v45, v77, v66
	v_mul_f32_e32 v47, 0.15915494, v45
	v_rndne_f32_e32 v47, v47
	v_fma_f32 v47, v45, 0.15915494, -v47
	v_sin_f32_e32 v45, v47
	v_cos_f32_e32 v47, v47
	v_pk_mul_f32 v[68:69], v[44:45], v[10:11]
	v_pk_mul_f32 v[10:11], v[46:47], v[10:11]
	v_pk_fma_f32 v[68:69], v[46:47], v[42:43], v[68:69] neg_lo:[0,0,1] neg_hi:[0,0,1]
	v_pk_fma_f32 v[10:11], v[44:45], v[42:43], v[10:11]
	v_mul_f32_e32 v42, v82, v66
	v_mul_f32_e32 v43, 0.15915494, v42
	v_rndne_f32_e32 v43, v43
	v_fma_f32 v43, v42, 0.15915494, -v43
	v_sin_f32_e32 v42, v43
	v_cos_f32_e32 v44, v43
	v_mul_f32_e32 v43, v83, v66
	v_mul_f32_e32 v45, 0.15915494, v43
	v_rndne_f32_e32 v45, v45
	v_fma_f32 v45, v43, 0.15915494, -v45
	v_sin_f32_e32 v43, v45
	v_cos_f32_e32 v45, v45
	v_pk_mul_f32 v[46:47], v[42:43], v[14:15]
	v_pk_mul_f32 v[14:15], v[44:45], v[14:15]
	v_pk_fma_f32 v[46:47], v[44:45], v[40:41], v[46:47] neg_lo:[0,0,1] neg_hi:[0,0,1]
	v_pk_fma_f32 v[14:15], v[42:43], v[40:41], v[14:15]
	v_mul_f32_e32 v40, v67, v66
	v_mul_f32_e32 v41, 0.15915494, v40
	v_rndne_f32_e32 v41, v41
	v_fma_f32 v41, v40, 0.15915494, -v41
	v_sin_f32_e32 v40, v41
	v_cos_f32_e32 v42, v41
	v_mul_f32_e32 v41, v84, v66
	v_mul_f32_e32 v43, 0.15915494, v41
	v_rndne_f32_e32 v43, v43
	v_fma_f32 v43, v41, 0.15915494, -v43
	v_sin_f32_e32 v41, v43
	v_cos_f32_e32 v43, v43
	v_pk_mul_f32 v[44:45], v[40:41], v[0:1]
	v_pk_mul_f32 v[0:1], v[42:43], v[0:1]
	v_pk_fma_f32 v[44:45], v[42:43], v[38:39], v[44:45] neg_lo:[0,0,1] neg_hi:[0,0,1]
	v_pk_fma_f32 v[0:1], v[40:41], v[38:39], v[0:1]
	v_mul_f32_e32 v38, v85, v66
	v_mul_f32_e32 v39, 0.15915494, v38
	v_rndne_f32_e32 v39, v39
	v_fma_f32 v39, v38, 0.15915494, -v39
	v_sin_f32_e32 v38, v39
	v_cos_f32_e32 v40, v39
	v_mul_f32_e32 v39, v86, v66
	v_mul_f32_e32 v41, 0.15915494, v39
	v_rndne_f32_e32 v41, v41
	v_fma_f32 v41, v39, 0.15915494, -v41
	v_sin_f32_e32 v39, v41
	v_cos_f32_e32 v41, v41
	v_pk_mul_f32 v[42:43], v[38:39], v[2:3]
	v_pk_mul_f32 v[2:3], v[40:41], v[2:3]
	v_pk_fma_f32 v[42:43], v[40:41], v[34:35], v[42:43] neg_lo:[0,0,1] neg_hi:[0,0,1]
	v_pk_fma_f32 v[2:3], v[38:39], v[34:35], v[2:3]
	v_mul_f32_e32 v34, v87, v66
	v_mul_f32_e32 v35, 0.15915494, v34
	v_rndne_f32_e32 v35, v35
	v_fma_f32 v35, v34, 0.15915494, -v35
	v_sin_f32_e32 v34, v35
	v_cos_f32_e32 v38, v35
	v_mul_f32_e32 v35, v88, v66
	v_mul_f32_e32 v39, 0.15915494, v35
	v_rndne_f32_e32 v39, v39
	v_fma_f32 v39, v35, 0.15915494, -v39
	v_sin_f32_e32 v35, v39
	v_cos_f32_e32 v39, v39
	v_pk_mul_f32 v[40:41], v[34:35], v[4:5]
	v_pk_mul_f32 v[4:5], v[38:39], v[4:5]
	v_pk_fma_f32 v[40:41], v[38:39], v[32:33], v[40:41] neg_lo:[0,0,1] neg_hi:[0,0,1]
	v_pk_fma_f32 v[4:5], v[34:35], v[32:33], v[4:5]
	v_mul_f32_e32 v32, v89, v66
	v_mul_f32_e32 v33, 0.15915494, v32
	v_rndne_f32_e32 v33, v33
	v_fma_f32 v33, v32, 0.15915494, -v33
	v_sin_f32_e32 v32, v33
	v_cos_f32_e32 v34, v33
	v_mul_f32_e32 v33, v90, v66
	v_mul_f32_e32 v35, 0.15915494, v33
	v_rndne_f32_e32 v35, v35
	v_fma_f32 v35, v33, 0.15915494, -v35
	v_sin_f32_e32 v33, v35
	v_cos_f32_e32 v35, v35
	v_pk_mul_f32 v[38:39], v[32:33], v[6:7]
	s_nop 0
	v_pk_fma_f32 v[38:39], v[34:35], v[16:17], v[38:39] neg_lo:[0,0,1] neg_hi:[0,0,1]
	v_pk_mul_f32 v[6:7], v[34:35], v[6:7]
	v_mov_b64_e32 v[34:35], v[42:43]
	v_pk_fma_f32 v[6:7], v[32:33], v[16:17], v[6:7]
	v_mov_b64_e32 v[16:17], v[38:39]
	v_mov_b64_e32 v[32:33], v[40:41]
	v_mov_b64_e32 v[38:39], v[44:45]
	v_mov_b64_e32 v[40:41], v[46:47]
	v_mov_b64_e32 v[42:43], v[68:69]
	v_mov_b64_e32 v[44:45], v[70:71]
	v_mov_b64_e32 v[46:47], v[50:51]
	v_mov_b64_e32 v[50:51], v[54:55]
	v_mov_b64_e32 v[54:55], v[58:59]
	v_mov_b64_e32 v[58:59], v[62:63]
	v_mov_b64_e32 v[62:63], v[64:65]
	v_mov_b64_e32 v[64:65], v[60:61]
	v_mov_b64_e32 v[60:61], v[56:57]
	v_mov_b64_e32 v[56:57], v[52:53]
	v_mov_b64_e32 v[70:71], v[48:49]

; #define WAIT_BAR() asm volatile("s_waitcnt vmcnt(0) lgkmcnt(0)\n\ts_barrier" ::: "memory")
; template <int DQ, int MODE>
; __device__ __forceinline__ void attn_unit(const Args& a, char* lds, const int wave0) {
;     ...
;   int kx[4];
; #pragma unroll
;   for (int q = 0; q < 4; ++q) kx[q] = (int)(uintptr_t)K_lds + r32 * (DQ * 2) + ((q * 32 + hi * 16) ^ ((r32 & 7) << 4));
;     ...
;   DMA(0); DMA(1);
;   f32x16 negm = f32x16{}; asm volatile("" : "+v"(negm));
;   WAIT_BAR();
.LBB0_770:
	v_lshlrev_b32_e32 v8, 4, v73
	s_mov_b32 s4, 0xc000
	v_lshl_add_u32 v56, v161, 8, s4
	v_mov_b32_e32 v16, v195
	v_mov_b32_e32 v17, v195
	v_mov_b32_e32 v18, v195
	v_mov_b32_e32 v19, v195
	v_mov_b32_e32 v20, v195
	v_mov_b32_e32 v21, v195
	v_mov_b32_e32 v22, v195
	v_mov_b32_e32 v23, v195
	v_mov_b32_e32 v24, v195
	v_mov_b32_e32 v25, v195
	v_mov_b32_e32 v26, v195
	v_mov_b32_e32 v27, v195
	v_mov_b32_e32 v28, v195
	v_mov_b32_e32 v29, v195
	v_mov_b32_e32 v30, v195
	v_mov_b32_e32 v31, v195
	s_waitcnt vmcnt(0) lgkmcnt(0)
	s_barrier
; template <bool FIRST> __device__ __forceinline__ void partialSM(f32x16& p0, f32x16& p1, float& m_reg, float& alpha, f32x16& negm, const float thr) {
;   float pmax = p0[0];
; #pragma unroll
;   for (int r = 1; r < 16; ++r) pmax = fmaxf(pmax, p0[r]);
; #pragma unroll
;   for (int r = 0; r < 16; ++r) pmax = fmaxf(pmax, p1[r]);
;   { auto rr = __builtin_amdgcn_permlane32_swap(__float_as_uint(pmax), __float_as_uint(pmax), false, false);
;     pmax = fmaxf(__uint_as_float(rr[0]), __uint_as_float(rr[1])); }
;   alpha = 1.f;
;   if (FIRST || !__builtin_expect(__all(pmax <= thr), 1)) {
;     const float delta = FIRST ? pmax : fmaxf(pmax, 0.f);
;     m_reg += delta; if (!FIRST) alpha = __builtin_amdgcn_exp2f(-delta);
; #pragma unroll
;     for (int r = 0; r < 16; ++r) { p0[r] -= delta; p1[r] -= delta; }
;     const float nm = -m_reg;
; #pragma unroll
;     for (int r = 0; r < 16; ++r) negm[r] = nm;
;     asm volatile("" : "+v"(negm));
;   }
; #pragma unroll
;   for (int r = 0; r < 16; ++r) p0[r] = __builtin_amdgcn_exp2f(p0[r]);
; template <int DQ> __device__ __forceinline__ void qkt(f32x16& p0, f32x16& p1, const int (&kx)[4], int koff, const bf16x8* qr, const f32x16& negm) {
;   lds_b128_ptr k0 = (lds_b128_ptr)(unsigned)(kx[0] + koff), k1 = (lds_b128_ptr)(unsigned)(kx[1] + koff), k2 = (lds_b128_ptr)(unsigned)(kx[2] + koff), k3 = (lds_b128_ptr)(unsigned)(kx[3] + koff);
; #pragma unroll
;   for (int d0 = 0; d0 < DQ / 16; ++d0) { lds_b128_ptr kp = (d0 & 3) == 0 ? k0 : (d0 & 3) == 1 ? k1 : (d0 & 3) == 2 ? k2 : k3;
;     const bf16x8 b0 = kp[(d0 >> 2) * 8];
;     const bf16x8 b1 = kp[(d0 >> 2) * 8 + 32 * DQ * 2 / 16];
;     if (d0 == 0) { p0 = __builtin_amdgcn_mfma_f32_32x32x16_bf16(b0, qr[0], negm, 0, 0, 0); p1 = __builtin_amdgcn_mfma_f32_32x32x16_bf16(b1, qr[0], negm, 0, 0, 0); }
;     else { p0 = __builtin_amdgcn_mfma_f32_32x32x16_bf16(b0, qr[d0], p0, 0, 0, 0); p1 = __builtin_amdgcn_mfma_f32_32x32x16_bf16(b1, qr[d0], p1, 0, 0, 0); } }
; }
	ds_read_b128 v[0:3], v176
	ds_read_b128 v[4:7], v176 offset:128
	s_waitcnt vmcnt(7) lgkmcnt(1)
	v_mfma_f32_32x32x16_bf16 v[32:47], v[0:3], v[144:147], v[16:31]
	ds_read_b128 v[0:3], v176 offset:8192
	v_and_b32_e32 v57, 0x70, v8
	v_bitop3_b32 v8, v194, v57, 32 bitop3:0x36
	v_add_u32_e32 v181, v8, v56
	ds_read_b128 v[8:11], v176 offset:8320
	v_bitop3_b32 v48, v194, v57, 64 bitop3:0x36
	v_add_u32_e32 v178, v48, v56
	s_waitcnt lgkmcnt(1)
	v_mfma_f32_32x32x16_bf16 v[16:31], v[0:3], v[144:147], v[16:31]
	ds_read_b128 v[0:3], v181
	ds_read_b128 v[12:15], v181 offset:128
	ds_read_b128 v[48:51], v181 offset:8320
	s_movk_i32 s4, 0x60
	v_bitop3_b32 v57, v194, v57, s4 bitop3:0x36
	v_add_u32_e32 v177, v57, v56
	s_mov_b32 s4, 2
	s_mov_b32 s46, 3
	s_waitcnt vmcnt(6) lgkmcnt(2)
	v_mfma_f32_32x32x16_bf16 v[32:47], v[0:3], v[152:155], v[32:47]
	ds_read_b128 v[0:3], v181 offset:8192
	s_mov_b32 s47, 1
	s_mov_b32 s64, 0
	v_cmp_gt_u32_e64 s[38:39], 32, v170
	v_add_u32_e32 v186, 0x8000, v179
	v_add_u32_e32 v189, 0xc000, v179
	v_mov_b32_e32 v174, 0
	s_waitcnt lgkmcnt(0)
	v_mfma_f32_32x32x16_bf16 v[16:31], v[0:3], v[152:155], v[16:31]
	ds_read_b128 v[0:3], v178
	ds_read_b128 v[52:55], v178 offset:128
	ds_read_b128 v[56:59], v178 offset:8320
	v_mov_b32_e32 v190, 1.0
	s_waitcnt vmcnt(5) lgkmcnt(2)
	v_mfma_f32_32x32x16_bf16 v[32:47], v[0:3], v[148:151], v[32:47]
	ds_read_b128 v[0:3], v178 offset:8192
	s_waitcnt lgkmcnt(0)
	v_mfma_f32_32x32x16_bf16 v[16:31], v[0:3], v[148:151], v[16:31]
	ds_read_b128 v[0:3], v177
	ds_read_b128 v[60:63], v177 offset:128
	s_waitcnt vmcnt(4) lgkmcnt(1)
	v_mfma_f32_32x32x16_bf16 v[32:47], v[0:3], v[156:159], v[32:47]
	ds_read_b128 v[0:3], v177 offset:8192
	ds_read_b128 v[64:67], v177 offset:8320
	s_waitcnt vmcnt(3)
	v_mfma_f32_32x32x16_bf16 v[32:47], v[4:7], v[140:143], v[32:47]
	v_mov_b32_e32 v4, v195
	v_mov_b32_e32 v5, v195
	v_mov_b32_e32 v6, v195
	v_mov_b32_e32 v7, v195
	s_waitcnt lgkmcnt(1)
	v_mfma_f32_32x32x16_bf16 v[16:31], v[0:3], v[156:159], v[16:31]
	v_and_b32_e32 v0, 0x3fffffc0, v72
	v_lshl_add_u32 v172, v0, 2, s5
	v_lshlrev_b32_e32 v0, 3, v170
	v_lshlrev_b32_e32 v1, 4, v170
	v_and_b32_e32 v183, 0xc0, v1
	v_lshlrev_b32_e32 v1, 1, v170
	v_and_b32_e32 v185, 0x100, v0
	s_waitcnt vmcnt(2)
	v_mfma_f32_32x32x16_bf16 v[32:47], v[12:15], v[132:135], v[32:47]
	v_and_b32_e32 v182, 24, v0
	v_and_b32_e32 v184, 32, v1
	v_mov_b32_e32 v14, v195
	v_mov_b32_e32 v15, v195
	v_mov_b32_e32 v0, v195
	v_mov_b32_e32 v1, v195
	v_mov_b32_e32 v2, v195
	v_mfma_f32_32x32x16_bf16 v[16:31], v[8:11], v[140:143], v[16:31]
	v_mov_b32_e32 v3, v195
	v_mov_b32_e32 v8, v195
	v_mov_b32_e32 v9, v195
	v_mov_b32_e32 v10, v195
	v_mov_b32_e32 v11, v195
	v_mov_b32_e32 v12, v195
	v_mov_b32_e32 v13, v195
	s_waitcnt vmcnt(1)
	v_mfma_f32_32x32x16_bf16 v[32:47], v[52:55], v[136:139], v[32:47]
	v_lshl_add_u32 v173, v161, 2, v172
	v_mfma_f32_32x32x16_bf16 v[16:31], v[48:51], v[132:135], v[16:31]
	s_waitcnt vmcnt(0)
	v_mfma_f32_32x32x16_bf16 v[32:47], v[60:63], v[128:131], v[32:47]
	v_mfma_f32_32x32x16_bf16 v[16:31], v[56:59], v[136:139], v[16:31]
	s_nop 10
	v_max_f32_e32 v48, v33, v33
	v_max_f32_e32 v49, v32, v32
	v_max_f32_e32 v48, v49, v48
	v_max3_f32 v48, v48, v34, v35
	v_max3_f32 v48, v48, v36, v37
	v_max3_f32 v48, v48, v38, v39
	v_max3_f32 v48, v48, v40, v41
	s_waitcnt lgkmcnt(0)
	v_mfma_f32_32x32x16_bf16 v[16:31], v[64:67], v[128:131], v[16:31]
	v_max3_f32 v48, v48, v42, v43
	v_max3_f32 v48, v48, v44, v45
	v_max3_f32 v48, v48, v46, v47
	s_nop 8
	v_max3_f32 v48, v48, v16, v17
	v_max3_f32 v48, v48, v18, v19
	v_max3_f32 v48, v48, v20, v21
	v_max3_f32 v48, v48, v22, v23
	v_max3_f32 v48, v48, v24, v25
	v_max3_f32 v48, v48, v26, v27
	v_max3_f32 v48, v48, v28, v29
	v_max3_f32 v48, v48, v30, v31
	v_mov_b32_e32 v49, v48
	s_nop 1
	v_permlane32_swap_b32_e32 v48, v49
	v_max_f32_e32 v49, v49, v49
	v_max_f32_e32 v48, v48, v48
	v_max_f32_e32 v48, v48, v49
	v_sub_f32_e32 v32, v32, v48
	v_sub_f32_e32 v33, v33, v48
	v_sub_f32_e32 v34, v34, v48
	v_sub_f32_e32 v35, v35, v48
	v_sub_f32_e32 v36, v36, v48
	v_sub_f32_e32 v37, v37, v48
	v_sub_f32_e32 v38, v38, v48
	v_sub_f32_e32 v39, v39, v48
	v_sub_f32_e32 v40, v40, v48
	v_sub_f32_e32 v41, v41, v48
	v_sub_f32_e32 v42, v42, v48
	v_sub_f32_e32 v43, v43, v48
	v_sub_f32_e32 v44, v44, v48
	v_sub_f32_e32 v45, v45, v48
	v_sub_f32_e32 v46, v46, v48
	v_sub_f32_e32 v47, v47, v48
	v_exp_f32_e32 v218, v32
	v_exp_f32_e32 v219, v33
	v_exp_f32_e32 v215, v34
	v_exp_f32_e32 v217, v35
	v_exp_f32_e32 v213, v36
	v_exp_f32_e32 v216, v37
	v_exp_f32_e32 v212, v38
	v_exp_f32_e32 v214, v39
	v_exp_f32_e32 v208, v40
	v_exp_f32_e32 v210, v41
	v_exp_f32_e32 v206, v42
	v_exp_f32_e32 v209, v43
	v_exp_f32_e32 v204, v44
	v_exp_f32_e32 v207, v45
	v_exp_f32_e32 v203, v46
	v_exp_f32_e32 v205, v47
	v_add_f32_e32 v175, 0, v48
	v_sub_f32_e32 v80, v16, v48
	v_or_b32_e32 v16, v185, v183
	v_sub_f32_e32 v95, v31, v48
	v_sub_f32_e32 v94, v30, v48
	v_sub_f32_e32 v93, v29, v48
	v_sub_f32_e32 v92, v28, v48
	v_sub_f32_e32 v91, v27, v48
	v_sub_f32_e32 v90, v26, v48
	v_sub_f32_e32 v89, v25, v48
	v_sub_f32_e32 v88, v24, v48
	v_sub_f32_e32 v87, v23, v48
	v_sub_f32_e32 v86, v22, v48
	v_sub_f32_e32 v85, v21, v48
	v_sub_f32_e32 v84, v20, v48
	v_sub_f32_e32 v83, v19, v48
	v_sub_f32_e32 v82, v18, v48
	v_sub_f32_e32 v81, v17, v48
	v_xor_b32_e32 v64, 0x80000000, v175
	v_or3_b32 v187, v16, v184, v182
	v_mov_b64_e32 v[62:63], v[14:15]
	v_mov_b64_e32 v[46:47], v[14:15]
	v_mov_b64_e32 v[30:31], v[14:15]
	v_mov_b32_e32 v65, v64
	v_mov_b32_e32 v66, v64
	v_mov_b32_e32 v67, v64
	v_mov_b32_e32 v68, v64
	v_mov_b32_e32 v69, v64
	v_mov_b32_e32 v70, v64
	v_mov_b32_e32 v71, v64
	v_mov_b32_e32 v72, v64
	v_mov_b32_e32 v73, v64
	v_mov_b32_e32 v74, v64
	v_mov_b32_e32 v75, v64
	v_mov_b32_e32 v76, v64
	v_mov_b32_e32 v77, v64
	v_mov_b32_e32 v78, v64
	v_mov_b32_e32 v79, v64
	v_or_b32_e32 v188, 0x4000, v187
	v_mov_b64_e32 v[60:61], v[12:13]
	v_mov_b64_e32 v[58:59], v[10:11]
	v_mov_b64_e32 v[56:57], v[8:9]
	v_mov_b64_e32 v[54:55], v[6:7]
	v_mov_b64_e32 v[52:53], v[4:5]
	v_mov_b64_e32 v[50:51], v[2:3]
	v_mov_b64_e32 v[48:49], v[0:1]
	v_mov_b64_e32 v[44:45], v[12:13]
	v_mov_b64_e32 v[42:43], v[10:11]
	v_mov_b64_e32 v[40:41], v[8:9]
	v_mov_b64_e32 v[38:39], v[6:7]
	v_mov_b64_e32 v[36:37], v[4:5]
	v_mov_b64_e32 v[34:35], v[2:3]
	v_mov_b64_e32 v[32:33], v[0:1]
	v_mov_b64_e32 v[28:29], v[12:13]
	v_mov_b64_e32 v[26:27], v[10:11]
	v_mov_b64_e32 v[24:25], v[8:9]
	v_mov_b64_e32 v[22:23], v[6:7]
	v_mov_b64_e32 v[20:21], v[4:5]
	v_mov_b64_e32 v[18:19], v[2:3]
	v_mov_b64_e32 v[16:17], v[0:1]
